# speedup vs baseline: 1.0285x; 1.0078x over previous
; __device__ __forceinline__ uint4 ldg16(const void* p) { const u32x4 v = *(const __attribute__((address_space(1))) u32x4*)(p); return make_uint4(v.x, v.y, v.z, v.w); }
; __device__ __forceinline__ void attn_phase(const Params& p, char* shmc, int tid, int wv) {
;     ...
;     const int h = tile & 15, qb = 255 - (tile >> 4);
;     {
;       const int row = tid >> 3, c0 = (tid & 7) * 16;
;       const u16* src = QKV + ((long)qb * 64 + row) * 6144 + h * 128 + c0;
;       *(uint4*)&Qs[row * 136 + c0] = ldg16(src);
;       *(uint4*)&Qs[row * 136 + c0 + 8] = ldg16(src + 8);
;     }
;     float carry = 0.f;
;     f32x4 oacc[4];
; #pragma unroll
;     for (int i = 0; i < 4; ++i) oacc[i] = f32x4{0.f, 0.f, 0.f, 0.f};
;     const int krow = tid >> 3, kc0 = (tid & 7) * 16, vkey = tid & 63, vd0 = wv * 16;
;     uint4 ka, kb4, va, vb;
;     {
;       const u16* src = QKV + ((long)qb * 64 + krow) * 6144 + 2048 + h * 128 + kc0;
;       ka = ldg16(src); kb4 = ldg16(src + 8);
;       const u16* vs = QKV + ((long)qb * 64 + vkey) * 6144 + 4096 + h * 128 + vd0;
;       va = ldg16(vs); vb = ldg16(vs + 8);
;     }
.LBB0_308:
	s_ashr_i32 s18, s7, 4
	s_sub_i32 s88, 0xff, s18
	s_lshl_b64 s[48:49], s[88:89], 6
	v_lshl_add_u64 v[0:1], s[48:49], 0, v[44:45]
	v_mad_u64_u32 v[2:3], s[14:15], v0, s71, v[40:41]
	s_lshl_b32 s14, s7, 7
	s_and_b32 s59, s14, 0x780
	v_mad_i32_i24 v3, v1, s71, v3
	s_lshl_b32 s14, s59, 1
	s_mov_b32 s15, s89
	v_lshl_add_u64 v[0:1], v[2:3], 0, s[14:15]
	v_mov_b32_e32 v57, v213
	v_lshl_add_u64 v[8:9], v[0:1], 0, v[56:57]
	global_load_dwordx4 v[0:3], v[8:9], off offset:16
	global_load_dwordx4 v[4:7], v[8:9], off
	s_mov_b32 s37, s89
	v_lshl_add_u64 v[12:13], v[8:9], 0, s[54:55]
	v_mov_b32_e32 v59, 0
	v_lshl_add_u32 v90, s88, 6, v44
	s_add_i32 s61, s18, 0xffffff01
	s_mov_b32 s68, s88
	v_mov_b32_e32 v16, v59
	v_mov_b32_e32 v17, v59
	v_mov_b32_e32 v18, v59
	v_mov_b32_e32 v19, v59
	v_mov_b32_e32 v20, v59
	v_mov_b32_e32 v21, v59
	v_mov_b32_e32 v22, v59
	v_mov_b32_e32 v23, v59
	v_mov_b32_e32 v24, v59
	v_mov_b32_e32 v25, v59
	v_mov_b32_e32 v26, v59
	v_mov_b32_e32 v27, v59
	v_mov_b32_e32 v28, v59
	v_mov_b32_e32 v29, v59
	v_mov_b32_e32 v30, v59
	v_mov_b32_e32 v31, v59
	s_waitcnt vmcnt(0)
	ds_write_b128 v43, v[4:7]
	ds_write_b128 v43, v[0:3] offset:16
	s_waitcnt lgkmcnt(0)
	s_barrier
	ds_read_b128 v[160:163], v47
	ds_read_b128 v[164:167], v47 offset:64
	ds_read_b128 v[168:171], v47 offset:128
	ds_read_b128 v[172:175], v47 offset:192
	v_or_b32_e32 v0, s48, v42
	v_mad_u64_u32 v[0:1], s[16:17], v0, s71, v[40:41]
	v_mad_u32_u24 v1, s49, v237, v1
	v_lshl_add_u64 v[0:1], v[0:1], 0, s[14:15]
	v_lshl_add_u64 v[0:1], v[0:1], 0, s[36:37]
	v_lshl_add_u64 v[2:3], v[0:1], 0, s[46:47]
	v_add_co_u32_e32 v0, vcc, s67, v0
	s_lshl_b32 s14, s18, 6
	s_nop 0
	v_addc_co_u32_e32 v1, vcc, 0, v1, vcc
	v_add_co_u32_e32 v8, vcc, s66, v8
	global_load_dwordx4 v[4:7], v[0:1], off
	s_nop 0
	global_load_dwordx4 v[0:3], v[2:3], off offset:16
	v_addc_co_u32_e32 v9, vcc, 0, v9, vcc
	global_load_dwordx4 v[8:11], v[8:9], off
	s_nop 0
	global_load_dwordx4 v[12:15], v[12:13], off offset:16
	v_subrev_u32_e32 v91, s14, v81
	v_sub_u32_e64 v212, s68, 1 clamp
	v_lshlrev_b64 v[144:145], 6, v[212:213]
	v_lshl_add_u64 v[146:147], v[144:145], 0, v[44:45]
	v_mad_u64_u32 v[148:149], s[18:19], v146, s71, v[40:41]
	v_mad_i32_i24 v149, v147, s71, v149
	s_lshl_b32 s16, s59, 1
	s_mov_b32 s17, s89
	v_lshl_add_u64 v[146:147], v[148:149], 0, s[16:17]
	v_lshl_add_u64 v[146:147], v[146:147], 0, v[56:57]
	v_lshl_add_u64 v[148:149], v[146:147], 0, s[54:55]
	v_add_co_u32_e32 v146, vcc, s66, v146
	v_or_b32_e32 v144, v144, v42
	s_nop 0
	v_addc_co_u32_e32 v147, vcc, 0, v147, vcc
	global_load_dwordx4 v[152:155], v[146:147], off
	global_load_dwordx4 v[156:159], v[148:149], off offset:16
	v_mad_u64_u32 v[146:147], s[18:19], v144, s71, v[40:41]
	v_mad_u32_u24 v147, v145, s71, v147
	v_lshl_add_u64 v[144:145], v[146:147], 0, s[16:17]
	v_lshl_add_u64 v[144:145], v[144:145], 0, s[36:37]
	v_lshl_add_u64 v[146:147], v[144:145], 0, s[46:47]
	v_add_co_u32_e32 v144, vcc, s67, v144
	s_nop 0
	v_addc_co_u32_e32 v145, vcc, 0, v145, vcc
	global_load_dwordx4 v[148:151], v[144:145], off
	s_nop 0
	global_load_dwordx4 v[144:147], v[146:147], off offset:16
	s_branch .LBB0_311

; __device__ __forceinline__ uint4 ldg16(const void* p) { const u32x4 v = *(const __attribute__((address_space(1))) u32x4*)(p); return make_uint4(v.x, v.y, v.z, v.w); }
; __device__ __forceinline__ void attn_phase(const Params& p, char* shmc, int tid, int wv) {
;     ...
;       {
;         *(uint4*)&Ks[krow * 136 + kc0] = ka;
;         *(uint4*)&Ks[krow * 136 + kc0 + 8] = kb4;
;         const unsigned vw[8] = {va.x, va.y, va.z, va.w, vb.x, vb.y, vb.z, vb.w};
; #pragma unroll
;         for (int i = 0; i < 8; ++i) { Vt[(vd0 + 2 * i) * 72 + vkey] = (u16)(vw[i] & 0xffffu); Vt[(vd0 + 2 * i + 1) * 72 + vkey] = (u16)(vw[i] >> 16); }
;       }
;       __syncthreads();
;       {
;         const int kn = kb > 0 ? kb - 1 : 0;
;         const u16* src = QKV + ((long)kn * 64 + krow) * 6144 + 2048 + h * 128 + kc0;
;         ka = ldg16(src); kb4 = ldg16(src + 8);
;         const u16* vs = QKV + ((long)kn * 64 + vkey) * 6144 + 4096 + h * 128 + vd0;
;         va = ldg16(vs); vb = ldg16(vs + 8);
;       }
;       {
;         const int ntb = (wv >> 2) * 2;
;         f32x4 z[2] = {{0.f, 0.f, 0.f, 0.f}, {0.f, 0.f, 0.f, 0.f}};
; #pragma unroll
;         for (int kk = 0; kk < 4; ++kk) {
;           const bf16x8 a = *(const bf16x8*)&Qs[(16 * mt + r) * 136 + kk * 32 + quad * 8];
; #pragma unroll
;           for (int i = 0; i < 2; ++i) {
;             const bf16x8 b = *(const bf16x8*)&Ks[(16 * (ntb + i) + r) * 136 + kk * 32 + quad * 8];
;             z[i] = __builtin_amdgcn_mfma_f32_16x16x32_bf16(a, b, z[i], 0, 0, 0);
;           }
;         }
; #pragma unroll
;         for (int i = 0; i < 2; ++i)
; #pragma unroll
;           for (int j = 0; j < 4; ++j) Zs[(16 * mt + 4 * quad + j) * 68 + 16 * (ntb + i) + r] = z[i][j] * 0.08838834764831845f;
;       }
;       __syncthreads();
;       {
;         const int row = tid >> 3, part = tid & 7;
;         const float4 za = *(const float4*)&Zs[row * 68 + part * 8], zb = *(const float4*)&Zs[row * 68 + part * 8 + 4];
;         const float z[8] = {za.x, za.y, za.z, za.w, zb.x, zb.y, zb.z, zb.w};
;         const int qpos = qb * 64 + row, kpos0 = kb * 64 + part * 8;
;         float sp[8];
;         float ptot = 0.f;
; #pragma unroll
;         for (int i = 0; i < 8; ++i) {
;           const bool valid = (kpos0 + i) < qpos;
;           sp[i] = valid ? (fmaxf(z[i], 0.f) + __logf(1.f + __expf(-fabsf(z[i])))) : 0.f;
;           ptot += sp[i];
.LBB0_311:
	v_sub_u32_e64 v212, s68, 2 clamp
	s_waitcnt vmcnt(5)
	ds_write_b128 v43, v[8:11] offset:17408
	s_waitcnt vmcnt(4)
	ds_write_b128 v43, v[12:15] offset:17424
	ds_write_b128 v77, v[4:7] offset:34816
	ds_write_b128 v77, v[0:3] offset:34832
	v_lshlrev_b64 v[0:1], 6, v[212:213]
	v_lshl_add_u64 v[2:3], v[0:1], 0, v[44:45]
	v_mad_u64_u32 v[4:5], s[14:15], v2, s71, v[40:41]
	v_mad_i32_i24 v5, v3, s71, v5
	s_lshl_b32 s88, s59, 1
	v_lshl_add_u64 v[2:3], v[4:5], 0, s[88:89]
	v_lshl_add_u64 v[2:3], v[2:3], 0, v[56:57]
	v_lshl_add_u64 v[4:5], v[2:3], 0, s[54:55]
	v_add_co_u32_e32 v2, vcc, s66, v2
	v_or_b32_e32 v0, v0, v42
	s_nop 0
	v_addc_co_u32_e32 v3, vcc, 0, v3, vcc
	s_waitcnt lgkmcnt(0)
	s_barrier
	global_load_dwordx4 v[8:11], v[2:3], off
	global_load_dwordx4 v[12:15], v[4:5], off offset:16
	v_mad_u64_u32 v[2:3], s[14:15], v0, s71, v[40:41]
	v_mad_u32_u24 v3, v1, s71, v3
	v_lshl_add_u64 v[0:1], v[2:3], 0, s[88:89]
	v_lshl_add_u64 v[0:1], v[0:1], 0, s[36:37]
	v_lshl_add_u64 v[2:3], v[0:1], 0, s[46:47]
	v_add_co_u32_e32 v0, vcc, s67, v0
	v_add_u32_e32 v58, 0xd000, v84
	s_nop 0
	v_addc_co_u32_e32 v1, vcc, 0, v1, vcc
	global_load_dwordx4 v[4:7], v[0:1], off
	s_nop 0
	global_load_dwordx4 v[0:3], v[2:3], off offset:16
	ds_read_b128 v[112:115], v82 offset:17408
	ds_read_b128 v[128:131], v83 offset:17408
	ds_read_b128 v[116:119], v82 offset:17472
	ds_read_b128 v[132:135], v83 offset:17472
	ds_read_b128 v[120:123], v82 offset:17536
	ds_read_b128 v[136:139], v83 offset:17536
	ds_read_b128 v[124:127], v82 offset:17600
	ds_read_b128 v[140:143], v83 offset:17600
	s_waitcnt lgkmcnt(7)
	v_mfma_f32_16x16x32_bf16 v[36:39], v[160:163], v[112:115], 0
	s_waitcnt lgkmcnt(6)
	v_mfma_f32_16x16x32_bf16 v[32:35], v[160:163], v[128:131], 0
	s_waitcnt lgkmcnt(5)
	v_mfma_f32_16x16x32_bf16 v[36:39], v[164:167], v[116:119], v[36:39]
	s_waitcnt lgkmcnt(4)
	v_mfma_f32_16x16x32_bf16 v[32:35], v[164:167], v[132:135], v[32:35]
	s_waitcnt lgkmcnt(3)
	v_mfma_f32_16x16x32_bf16 v[36:39], v[168:171], v[120:123], v[36:39]
	s_waitcnt lgkmcnt(2)
	v_mfma_f32_16x16x32_bf16 v[32:35], v[168:171], v[136:139], v[32:35]
	s_waitcnt lgkmcnt(1)
	v_mfma_f32_16x16x32_bf16 v[36:39], v[172:175], v[124:127], v[36:39]
	s_waitcnt lgkmcnt(0)
	v_mfma_f32_16x16x32_bf16 v[32:35], v[172:175], v[140:143], v[32:35]
	s_nop 7
	v_mul_f32_e32 v36, 0x3db504f3, v36
	v_mul_f32_e32 v37, 0x3db504f3, v37
	ds_write2_b32 v58, v36, v37 offset1:68
	v_mul_f32_e32 v36, 0x3db504f3, v38
	v_mul_f32_e32 v37, 0x3db504f3, v39
	ds_write2_b32 v58, v36, v37 offset0:136 offset1:204
	v_mul_f32_e32 v32, 0x3db504f3, v32
	v_mul_f32_e32 v33, 0x3db504f3, v33
	v_add_u32_e32 v36, 0xd000, v85
	ds_write2_b32 v36, v32, v33 offset1:68
	v_mul_f32_e32 v32, 0x3db504f3, v34
	v_mul_f32_e32 v33, 0x3db504f3, v35
	ds_write2_b32 v36, v32, v33 offset0:136 offset1:204
	s_waitcnt lgkmcnt(0)
	s_barrier
	ds_read_b128 v[32:35], v51 offset:53248
	ds_read_b128 v[36:39], v51 offset:53264
	v_add_u32_e32 v58, -7, v91
	v_cmp_lt_i32_e32 vcc, v58, v90
	v_add_u32_e32 v58, -6, v91
	v_cmp_lt_i32_e64 s[14:15], v58, v90
	v_add_u32_e32 v58, -5, v91
	v_cmp_lt_i32_e64 s[16:17], v58, v90
	v_add_u32_e32 v58, -4, v91
	v_cmp_lt_i32_e64 s[18:19], v58, v90
	v_add_u32_e32 v58, -3, v91
	v_cmp_lt_i32_e64 s[20:21], v58, v90
	v_add_u32_e32 v58, -2, v91
	v_cmp_lt_i32_e64 s[22:23], v58, v90
	v_add_u32_e32 v58, -1, v91
	v_cmp_lt_i32_e64 s[24:25], v58, v90
	v_cmp_lt_i32_e64 s[26:27], v91, v90
	s_waitcnt lgkmcnt(0)
	v_mul_f32_e64 v96, |v32|, s74
	v_mul_f32_e64 v97, |v33|, s74
	v_mul_f32_e64 v98, |v34|, s74
	v_mul_f32_e64 v99, |v35|, s74
	v_mul_f32_e64 v100, |v36|, s74
	v_mul_f32_e64 v101, |v37|, s74
	v_mul_f32_e64 v102, |v38|, s74
	v_mul_f32_e64 v103, |v39|, s74
	v_exp_f32_e32 v96, v96
	v_exp_f32_e32 v97, v97
	v_exp_f32_e32 v98, v98
	v_exp_f32_e32 v99, v99
	v_exp_f32_e32 v100, v100
	v_exp_f32_e32 v101, v101
	v_exp_f32_e32 v102, v102
	v_exp_f32_e32 v103, v103
	v_max_f32_e32 v60, v32, v32
	v_max_f32_e32 v62, v33, v33
	v_max_f32_e32 v64, v34, v34
	v_max_f32_e32 v66, v35, v35
	v_max_f32_e32 v68, v36, v36
	v_max_f32_e32 v70, v37, v37
	v_max_f32_e32 v72, v38, v38
	v_max_f32_e32 v74, v39, v39
	v_add_f32_e32 v96, 1.0, v96
	v_add_f32_e32 v97, 1.0, v97
	v_add_f32_e32 v98, 1.0, v98
	v_add_f32_e32 v99, 1.0, v99
	v_add_f32_e32 v100, 1.0, v100
	v_add_f32_e32 v101, 1.0, v101
	v_add_f32_e32 v102, 1.0, v102
	v_add_f32_e32 v103, 1.0, v103
	v_log_f32_e32 v96, v96
	v_log_f32_e32 v97, v97
	v_log_f32_e32 v98, v98
	v_log_f32_e32 v99, v99
	v_log_f32_e32 v100, v100
	v_log_f32_e32 v101, v101
	v_log_f32_e32 v102, v102
	v_log_f32_e32 v103, v103
	v_max_f32_e32 v60, 0, v60
	v_max_f32_e32 v62, 0, v62
	v_max_f32_e32 v64, 0, v64
	v_max_f32_e32 v66, 0, v66
	v_max_f32_e32 v68, 0, v68
	v_max_f32_e32 v70, 0, v70
	v_max_f32_e32 v72, 0, v72
	v_max_f32_e32 v74, 0, v74
	v_mul_f32_e32 v104, 0x3f317217, v96
	v_mul_f32_e32 v105, 0x3f317217, v97
	v_mul_f32_e32 v106, 0x3f317217, v98
	v_mul_f32_e32 v107, 0x3f317217, v99
	v_mul_f32_e32 v108, 0x3f317217, v100
	v_mul_f32_e32 v109, 0x3f317217, v101
	v_mul_f32_e32 v110, 0x3f317217, v102
	v_mul_f32_e32 v111, 0x3f317217, v103
	v_fma_f32 v104, v96, s75, -v104
	v_fma_f32 v105, v97, s75, -v105
	v_fma_f32 v106, v98, s75, -v106
	v_fma_f32 v107, v99, s75, -v107
	v_fma_f32 v108, v100, s75, -v108
	v_fma_f32 v109, v101, s75, -v109
	v_fma_f32 v110, v102, s75, -v110
	v_fma_f32 v111, v103, s75, -v111
	v_fmac_f32_e32 v104, 0x3377d1cf, v96
	v_fmac_f32_e32 v105, 0x3377d1cf, v97
	v_fmac_f32_e32 v106, 0x3377d1cf, v98
	v_fmac_f32_e32 v107, 0x3377d1cf, v99
	v_fmac_f32_e32 v108, 0x3377d1cf, v100
	v_fmac_f32_e32 v109, 0x3377d1cf, v101
	v_fmac_f32_e32 v110, 0x3377d1cf, v102
	v_fmac_f32_e32 v111, 0x3377d1cf, v103
	v_fmac_f32_e32 v104, 0x3f317217, v96
	v_fmac_f32_e32 v105, 0x3f317217, v97
	v_fmac_f32_e32 v106, 0x3f317217, v98
	v_fmac_f32_e32 v107, 0x3f317217, v99
	v_fmac_f32_e32 v108, 0x3f317217, v100
	v_fmac_f32_e32 v109, 0x3f317217, v101
	v_fmac_f32_e32 v110, 0x3f317217, v102
	v_fmac_f32_e32 v111, 0x3f317217, v103
	v_add_f32_e32 v60, v60, v104
	v_add_f32_e32 v62, v62, v105
	v_add_f32_e32 v64, v64, v106
	v_add_f32_e32 v66, v66, v107
	v_add_f32_e32 v68, v68, v108
	v_add_f32_e32 v70, v70, v109
	v_add_f32_e32 v72, v72, v110
	v_add_f32_e32 v74, v74, v111
	v_cndmask_b32_e32 v60, 0, v60, vcc
	v_cndmask_b32_e64 v62, 0, v62, s[14:15]
	v_cndmask_b32_e64 v64, 0, v64, s[16:17]
	v_cndmask_b32_e64 v66, 0, v66, s[18:19]
	v_cndmask_b32_e64 v68, 0, v68, s[20:21]
	v_cndmask_b32_e64 v70, 0, v70, s[22:23]
	v_cndmask_b32_e64 v72, 0, v72, s[24:25]
	v_cndmask_b32_e64 v74, 0, v74, s[26:27]
	v_add_f32_e32 v58, 0, v60
	v_add_f32_e32 v58, v58, v62
	v_add_f32_e32 v58, v58, v64
	v_add_f32_e32 v58, v58, v66
	v_add_f32_e32 v58, v58, v68
	v_add_f32_e32 v58, v58, v70
	v_add_f32_e32 v58, v58, v72
	v_add_f32_e32 v58, v58, v74
	ds_bpermute_b32 v61, v78, v58
	v_mov_b32_e32 v73, v74
	v_mov_b32_e32 v71, v72
	v_mov_b32_e32 v69, v70
	v_mov_b32_e32 v67, v68
	s_waitcnt lgkmcnt(0)
; __device__ __forceinline__ unsigned pack2(float a, float b) { const f32v2_ v = {a, b}; const bf16v2_ r = __builtin_convertvector(v, bf16v2_); return __builtin_bit_cast(unsigned, r); }
; __device__ __forceinline__ float shfl_idx(float v, int srclane) { return __int_as_float(__builtin_amdgcn_ds_bpermute(srclane << 2, __float_as_int(v))); }
; __device__ __forceinline__ void attn_phase(const Params& p, char* shmc, int tid, int wv) {
;     ...
;         float tot = ptot;
; #pragma unroll
;         for (int o = 1; o < 8; o <<= 1) { const float v = shfl_idx(tot, lane + o); if (part + o < 8) tot += v; }
;         float running = carry - (tot - ptot);
;         float a[8];
; #pragma unroll
;         for (int i = 7; i >= 0; --i) {
;           const bool valid = (kpos0 + i) < qpos;
;           a[i] = valid ? __expf(z[i] - sp[i] + running) : 0.f;
;           running -= sp[i];
;         }
;         const float all = shfl_idx(tot, lane & ~7);
;         carry -= all;
;         *(uint4*)&Ps[row * 72 + part * 8] = make_uint4(pack2(a[0], a[1]), pack2(a[2], a[3]), pack2(a[4], a[5]), pack2(a[6], a[7]));
;       }
;       __syncthreads();
;       {
;         const int ntb = (wv >> 2) * 4;
; #pragma unroll
;         for (int kk = 0; kk < 2; ++kk) {
;           const bf16x8 a = *(const bf16x8*)&Ps[(16 * mt + r) * 72 + kk * 32 + quad * 8];
; #pragma unroll
;           for (int i = 0; i < 4; ++i) {
;             const bf16x8 b = *(const bf16x8*)&Vt[(16 * (ntb + i) + r) * 72 + kk * 32 + quad * 8];
;             oacc[i] = __builtin_amdgcn_mfma_f32_16x16x32_bf16(a, b, oacc[i], 0, 0, 0);
;           }
;         }
;       }
;       const int more = __syncthreads_or(carry > -120.f);
;       if (!more) break;
	v_add_f32_e32 v61, v58, v61
	v_cndmask_b32_e64 v61, v61, v58, s[8:9]
	ds_bpermute_b32 v63, v79, v61
	v_mov_b32_e32 v65, v66
	s_bitcmp1_b32 exec_hi, 0
	s_waitcnt lgkmcnt(0)
	v_add_f32_e32 v63, v61, v63
	v_cndmask_b32_e64 v61, v61, v63, s[10:11]
	ds_bpermute_b32 v63, v80, v61
	s_waitcnt lgkmcnt(0)
	v_add_f32_e32 v63, v61, v63
	v_cndmask_b32_e64 v94, v61, v63, s[12:13]
	v_sub_f32_e32 v75, v94, v58
	v_mov_b32_e32 v58, v39
	v_pk_add_f32 v[92:93], v[58:59], v[74:75] neg_lo:[0,1] neg_hi:[0,1]
	v_mov_b32_e32 v63, v64
	v_add_f32_e32 v39, v92, v93
	v_mul_f32_e32 v39, 0x3fb8aa3b, v39
	v_exp_f32_e32 v39, v39
	v_mov_b32_e32 v61, v62
	v_cndmask_b32_e64 v58, 0, v39, s[26:27]
	v_mov_b32_e32 v39, v93
	v_pk_add_f32 v[38:39], v[38:39], v[72:73] neg_lo:[0,1] neg_hi:[0,1]
	s_nop 0
	v_add_f32_e32 v38, v38, v39
	v_mul_f32_e32 v38, 0x3fb8aa3b, v38
	v_exp_f32_e32 v38, v38
	s_nop 0
	v_cndmask_b32_e64 v73, 0, v38, s[24:25]
	v_mov_b32_e32 v38, v37
	v_pk_add_f32 v[38:39], v[38:39], v[70:71] neg_lo:[0,1] neg_hi:[0,1]
	s_nop 0
	v_add_f32_e32 v37, v38, v39
	v_mul_f32_e32 v37, 0x3fb8aa3b, v37
	v_exp_f32_e32 v37, v37
	s_nop 0
	v_cndmask_b32_e64 v38, 0, v37, s[22:23]
	v_mov_b32_e32 v37, v39
	v_pk_add_f32 v[36:37], v[36:37], v[68:69] neg_lo:[0,1] neg_hi:[0,1]
	s_nop 0
	v_add_f32_e32 v36, v36, v37
	v_mul_f32_e32 v36, 0x3fb8aa3b, v36
	v_exp_f32_e32 v36, v36
	s_nop 0
	v_cndmask_b32_e64 v39, 0, v36, s[20:21]
	v_mov_b32_e32 v36, v35
	v_pk_add_f32 v[36:37], v[36:37], v[66:67] neg_lo:[0,1] neg_hi:[0,1]
	s_nop 0
	v_add_f32_e32 v35, v36, v37
	v_mul_f32_e32 v35, 0x3fb8aa3b, v35
	v_exp_f32_e32 v35, v35
	s_nop 0
	v_cndmask_b32_e64 v36, 0, v35, s[18:19]
	v_mov_b32_e32 v35, v37
	v_pk_add_f32 v[34:35], v[34:35], v[64:65] neg_lo:[0,1] neg_hi:[0,1]
	s_nop 0
	v_add_f32_e32 v34, v34, v35
	v_mul_f32_e32 v34, 0x3fb8aa3b, v34
	v_exp_f32_e32 v34, v34
	s_nop 0
	v_cndmask_b32_e64 v37, 0, v34, s[16:17]
	v_mov_b32_e32 v34, v33
	v_pk_add_f32 v[34:35], v[34:35], v[62:63] neg_lo:[0,1] neg_hi:[0,1]
	s_nop 0
	v_add_f32_e32 v33, v34, v35
	v_mul_f32_e32 v33, 0x3fb8aa3b, v33
	v_exp_f32_e32 v33, v33
	s_nop 0
	v_cndmask_b32_e64 v34, 0, v33, s[14:15]
	v_mov_b32_e32 v33, v35
	v_pk_add_f32 v[32:33], v[32:33], v[60:61] neg_lo:[0,1] neg_hi:[0,1]
	v_cvt_pk_bf16_f32 v35, v73, v58
	v_add_f32_e32 v32, v32, v33
	v_mul_f32_e32 v32, 0x3fb8aa3b, v32
	v_exp_f32_e32 v32, v32
	v_cvt_pk_bf16_f32 v33, v37, v36
	ds_bpermute_b32 v60, v53, v94
	s_mov_b32 s14, 0xc2d00000
	v_cndmask_b32_e32 v32, 0, v32, vcc
	v_cvt_pk_bf16_f32 v32, v32, v34
	v_cvt_pk_bf16_f32 v34, v39, v38
	ds_write_b128 v55, v[32:35]
	s_waitcnt lgkmcnt(0)
	s_barrier
	ds_read_b128 v[96:99], v76
	ds_read_b64_tr_b16 v[104:105], v86 offset:34816
	ds_read_b64_tr_b16 v[106:107], v86 offset:35904
	ds_read_b64_tr_b16 v[108:109], v86 offset:34848
	ds_read_b64_tr_b16 v[110:111], v86 offset:35936
	ds_read_b64_tr_b16 v[112:113], v86 offset:34880
	ds_read_b64_tr_b16 v[114:115], v86 offset:35968
	ds_read_b64_tr_b16 v[116:117], v86 offset:34912
	ds_read_b64_tr_b16 v[118:119], v86 offset:36000
	ds_read_b128 v[100:103], v76 offset:64
	ds_read_b64_tr_b16 v[120:121], v86 offset:43520
	ds_read_b64_tr_b16 v[122:123], v86 offset:44608
	ds_read_b64_tr_b16 v[124:125], v86 offset:43552
	ds_read_b64_tr_b16 v[126:127], v86 offset:44640
	ds_read_b64_tr_b16 v[128:129], v86 offset:43584
	ds_read_b64_tr_b16 v[130:131], v86 offset:44672
	ds_read_b64_tr_b16 v[132:133], v86 offset:43616
	ds_read_b64_tr_b16 v[134:135], v86 offset:44704
	v_sub_f32_e32 v59, v59, v60
	v_cmp_lt_f32_e32 vcc, s14, v59
	s_waitcnt lgkmcnt(15)
	v_mfma_f32_16x16x32_bf16 v[16:19], v[96:99], v[104:107], v[16:19]
	s_waitcnt lgkmcnt(13)
	v_mfma_f32_16x16x32_bf16 v[20:23], v[96:99], v[108:111], v[20:23]
	s_waitcnt lgkmcnt(11)
	v_mfma_f32_16x16x32_bf16 v[24:27], v[96:99], v[112:115], v[24:27]
	s_waitcnt lgkmcnt(9)
	v_mfma_f32_16x16x32_bf16 v[28:31], v[96:99], v[116:119], v[28:31]
	s_waitcnt lgkmcnt(6)
	v_mfma_f32_16x16x32_bf16 v[16:19], v[100:103], v[120:123], v[16:19]
	s_waitcnt lgkmcnt(4)
	v_mfma_f32_16x16x32_bf16 v[20:23], v[100:103], v[124:127], v[20:23]
	s_waitcnt lgkmcnt(2)
	v_mfma_f32_16x16x32_bf16 v[24:27], v[100:103], v[128:131], v[24:27]
	s_waitcnt lgkmcnt(0)
	v_mfma_f32_16x16x32_bf16 v[28:31], v[100:103], v[132:135], v[28:31]
	s_cmp_lg_u64 vcc, 0
	s_cselect_b32 s16, 1, 0
	v_mov_b32_e32 v32, s16
	s_andn2_b64 vcc, exec, s[94:95]
	s_cbranch_vccnz .LBB0_310
	s_and_saveexec_b64 s[14:15], s[4:5]
	v_mov_b32_e32 v32, s16
	ds_write_b32 v213, v32
	s_or_b64 exec, exec, s[14:15]
	s_waitcnt lgkmcnt(0)
	s_barrier
	s_and_saveexec_b64 s[14:15], s[98:99]
	s_cbranch_execz .LBB0_309
	v_mbcnt_lo_u32_b32 v32, exec_lo, 0
	v_mbcnt_hi_u32_b32 v32, exec_hi, v32
	v_cmp_eq_u32_e32 vcc, 0, v32
	s_and_b64 exec, exec, vcc
	s_cbranch_execz .LBB0_309
	v_mov_b32_e32 v32, s16
	ds_or_b32 v213, v32
	s_branch .LBB0_309

; __device__ __forceinline__ uint4 ldg16(const void* p) { const u32x4 v = *(const __attribute__((address_space(1))) u32x4*)(p); return make_uint4(v.x, v.y, v.z, v.w); }
; __device__ __forceinline__ void attn_phase(const Params& p, char* shmc, int tid, int wv) {
;     ...
;       {
;         *(uint4*)&Ks[krow * 136 + kc0] = ka;
;         *(uint4*)&Ks[krow * 136 + kc0 + 8] = kb4;
;         const unsigned vw[8] = {va.x, va.y, va.z, va.w, vb.x, vb.y, vb.z, vb.w};
; #pragma unroll
;         for (int i = 0; i < 8; ++i) { Vt[(vd0 + 2 * i) * 72 + vkey] = (u16)(vw[i] & 0xffffu); Vt[(vd0 + 2 * i + 1) * 72 + vkey] = (u16)(vw[i] >> 16); }
;       }
;       __syncthreads();
;       {
;         const int kn = kb > 0 ? kb - 1 : 0;
;         const u16* src = QKV + ((long)kn * 64 + krow) * 6144 + 2048 + h * 128 + kc0;
;         ka = ldg16(src); kb4 = ldg16(src + 8);
;         const u16* vs = QKV + ((long)kn * 64 + vkey) * 6144 + 4096 + h * 128 + vd0;
;         va = ldg16(vs); vb = ldg16(vs + 8);
;       }
;       {
;         const int ntb = (wv >> 2) * 2;
;         f32x4 z[2] = {{0.f, 0.f, 0.f, 0.f}, {0.f, 0.f, 0.f, 0.f}};
; #pragma unroll
;         for (int kk = 0; kk < 4; ++kk) {
;           const bf16x8 a = *(const bf16x8*)&Qs[(16 * mt + r) * 136 + kk * 32 + quad * 8];
; #pragma unroll
;           for (int i = 0; i < 2; ++i) {
;             const bf16x8 b = *(const bf16x8*)&Ks[(16 * (ntb + i) + r) * 136 + kk * 32 + quad * 8];
;             z[i] = __builtin_amdgcn_mfma_f32_16x16x32_bf16(a, b, z[i], 0, 0, 0);
;           }
;         }
; #pragma unroll
;         for (int i = 0; i < 2; ++i)
; #pragma unroll
;           for (int j = 0; j < 4; ++j) Zs[(16 * mt + 4 * quad + j) * 68 + 16 * (ntb + i) + r] = z[i][j] * 0.08838834764831845f;
;       }
;       __syncthreads();
;       {
;         const int row = tid >> 3, part = tid & 7;
;         const float4 za = *(const float4*)&Zs[row * 68 + part * 8], zb = *(const float4*)&Zs[row * 68 + part * 8 + 4];
;         const float z[8] = {za.x, za.y, za.z, za.w, zb.x, zb.y, zb.z, zb.w};
;         const int qpos = qb * 64 + row, kpos0 = kb * 64 + part * 8;
;         float sp[8];
;         float ptot = 0.f;
; #pragma unroll
;         for (int i = 0; i < 8; ++i) {
;           const bool valid = (kpos0 + i) < qpos;
;           sp[i] = valid ? (fmaxf(z[i], 0.f) + __logf(1.f + __expf(-fabsf(z[i])))) : 0.f;
;           ptot += sp[i];
.Lat_bodyB:
	v_sub_u32_e64 v212, s68, 2 clamp
	s_waitcnt vmcnt(5)
	ds_write_b128 v43, v[152:155] offset:17408
	s_waitcnt vmcnt(4)
	ds_write_b128 v43, v[156:159] offset:17424
	ds_write_b128 v77, v[148:151] offset:34816
	ds_write_b128 v77, v[144:147] offset:34832
	v_lshlrev_b64 v[144:145], 6, v[212:213]
	v_lshl_add_u64 v[146:147], v[144:145], 0, v[44:45]
	v_mad_u64_u32 v[148:149], s[14:15], v146, s71, v[40:41]
	v_mad_i32_i24 v149, v147, s71, v149
	s_lshl_b32 s88, s59, 1
	v_lshl_add_u64 v[146:147], v[148:149], 0, s[88:89]
	v_lshl_add_u64 v[146:147], v[146:147], 0, v[56:57]
	v_lshl_add_u64 v[148:149], v[146:147], 0, s[54:55]
	v_add_co_u32_e32 v146, vcc, s66, v146
	v_or_b32_e32 v144, v144, v42
	s_nop 0
	v_addc_co_u32_e32 v147, vcc, 0, v147, vcc
	s_waitcnt lgkmcnt(0)
	s_barrier
	global_load_dwordx4 v[152:155], v[146:147], off
	global_load_dwordx4 v[156:159], v[148:149], off offset:16
	v_mad_u64_u32 v[146:147], s[14:15], v144, s71, v[40:41]
	v_mad_u32_u24 v147, v145, s71, v147
	v_lshl_add_u64 v[144:145], v[146:147], 0, s[88:89]
	v_lshl_add_u64 v[144:145], v[144:145], 0, s[36:37]
	v_lshl_add_u64 v[146:147], v[144:145], 0, s[46:47]
	v_add_co_u32_e32 v144, vcc, s67, v144
	v_add_u32_e32 v58, 0xd000, v84
	s_nop 0
	v_addc_co_u32_e32 v145, vcc, 0, v145, vcc
	global_load_dwordx4 v[148:151], v[144:145], off
	s_nop 0
	global_load_dwordx4 v[144:147], v[146:147], off offset:16
	ds_read_b128 v[112:115], v82 offset:17408
	ds_read_b128 v[128:131], v83 offset:17408
	ds_read_b128 v[116:119], v82 offset:17472
	ds_read_b128 v[132:135], v83 offset:17472
	ds_read_b128 v[120:123], v82 offset:17536
	ds_read_b128 v[136:139], v83 offset:17536
	ds_read_b128 v[124:127], v82 offset:17600
	ds_read_b128 v[140:143], v83 offset:17600
	s_waitcnt lgkmcnt(7)
	v_mfma_f32_16x16x32_bf16 v[36:39], v[160:163], v[112:115], 0
	s_waitcnt lgkmcnt(6)
	v_mfma_f32_16x16x32_bf16 v[32:35], v[160:163], v[128:131], 0
	s_waitcnt lgkmcnt(5)
	v_mfma_f32_16x16x32_bf16 v[36:39], v[164:167], v[116:119], v[36:39]
	s_waitcnt lgkmcnt(4)
	v_mfma_f32_16x16x32_bf16 v[32:35], v[164:167], v[132:135], v[32:35]
	s_waitcnt lgkmcnt(3)
	v_mfma_f32_16x16x32_bf16 v[36:39], v[168:171], v[120:123], v[36:39]
	s_waitcnt lgkmcnt(2)
	v_mfma_f32_16x16x32_bf16 v[32:35], v[168:171], v[136:139], v[32:35]
	s_waitcnt lgkmcnt(1)
	v_mfma_f32_16x16x32_bf16 v[36:39], v[172:175], v[124:127], v[36:39]
	s_waitcnt lgkmcnt(0)
	v_mfma_f32_16x16x32_bf16 v[32:35], v[172:175], v[140:143], v[32:35]
	s_nop 7
	v_mul_f32_e32 v36, 0x3db504f3, v36
	v_mul_f32_e32 v37, 0x3db504f3, v37
	ds_write2_b32 v58, v36, v37 offset1:68
	v_mul_f32_e32 v36, 0x3db504f3, v38
	v_mul_f32_e32 v37, 0x3db504f3, v39
	ds_write2_b32 v58, v36, v37 offset0:136 offset1:204
	v_mul_f32_e32 v32, 0x3db504f3, v32
	v_mul_f32_e32 v33, 0x3db504f3, v33
	v_add_u32_e32 v36, 0xd000, v85
	ds_write2_b32 v36, v32, v33 offset1:68
	v_mul_f32_e32 v32, 0x3db504f3, v34
	v_mul_f32_e32 v33, 0x3db504f3, v35
	ds_write2_b32 v36, v32, v33 offset0:136 offset1:204
	s_waitcnt lgkmcnt(0)
	s_barrier
	ds_read_b128 v[32:35], v51 offset:53248
	ds_read_b128 v[36:39], v51 offset:53264
	v_add_u32_e32 v58, -7, v91
	v_cmp_lt_i32_e32 vcc, v58, v90
	v_add_u32_e32 v58, -6, v91
	v_cmp_lt_i32_e64 s[14:15], v58, v90
	v_add_u32_e32 v58, -5, v91
	v_cmp_lt_i32_e64 s[16:17], v58, v90
	v_add_u32_e32 v58, -4, v91
	v_cmp_lt_i32_e64 s[18:19], v58, v90
	v_add_u32_e32 v58, -3, v91
	v_cmp_lt_i32_e64 s[20:21], v58, v90
	v_add_u32_e32 v58, -2, v91
	v_cmp_lt_i32_e64 s[22:23], v58, v90
	v_add_u32_e32 v58, -1, v91
	v_cmp_lt_i32_e64 s[24:25], v58, v90
	v_cmp_lt_i32_e64 s[26:27], v91, v90
	s_waitcnt lgkmcnt(0)
	v_mul_f32_e64 v96, |v32|, s74
	v_mul_f32_e64 v97, |v33|, s74
	v_mul_f32_e64 v98, |v34|, s74
	v_mul_f32_e64 v99, |v35|, s74
	v_mul_f32_e64 v100, |v36|, s74
	v_mul_f32_e64 v101, |v37|, s74
	v_mul_f32_e64 v102, |v38|, s74
	v_mul_f32_e64 v103, |v39|, s74
	v_exp_f32_e32 v96, v96
	v_exp_f32_e32 v97, v97
	v_exp_f32_e32 v98, v98
	v_exp_f32_e32 v99, v99
	v_exp_f32_e32 v100, v100
	v_exp_f32_e32 v101, v101
	v_exp_f32_e32 v102, v102
	v_exp_f32_e32 v103, v103
	v_max_f32_e32 v60, v32, v32
	v_max_f32_e32 v62, v33, v33
	v_max_f32_e32 v64, v34, v34
	v_max_f32_e32 v66, v35, v35
	v_max_f32_e32 v68, v36, v36
	v_max_f32_e32 v70, v37, v37
	v_max_f32_e32 v72, v38, v38
	v_max_f32_e32 v74, v39, v39
	v_add_f32_e32 v96, 1.0, v96
	v_add_f32_e32 v97, 1.0, v97
	v_add_f32_e32 v98, 1.0, v98
	v_add_f32_e32 v99, 1.0, v99
	v_add_f32_e32 v100, 1.0, v100
	v_add_f32_e32 v101, 1.0, v101
	v_add_f32_e32 v102, 1.0, v102
	v_add_f32_e32 v103, 1.0, v103
	v_log_f32_e32 v96, v96
	v_log_f32_e32 v97, v97
	v_log_f32_e32 v98, v98
	v_log_f32_e32 v99, v99
	v_log_f32_e32 v100, v100
	v_log_f32_e32 v101, v101
	v_log_f32_e32 v102, v102
	v_log_f32_e32 v103, v103
	v_max_f32_e32 v60, 0, v60
	v_max_f32_e32 v62, 0, v62
	v_max_f32_e32 v64, 0, v64
	v_max_f32_e32 v66, 0, v66
	v_max_f32_e32 v68, 0, v68
	v_max_f32_e32 v70, 0, v70
	v_max_f32_e32 v72, 0, v72
	v_max_f32_e32 v74, 0, v74
	v_mul_f32_e32 v104, 0x3f317217, v96
	v_mul_f32_e32 v105, 0x3f317217, v97
	v_mul_f32_e32 v106, 0x3f317217, v98
	v_mul_f32_e32 v107, 0x3f317217, v99
	v_mul_f32_e32 v108, 0x3f317217, v100
	v_mul_f32_e32 v109, 0x3f317217, v101
	v_mul_f32_e32 v110, 0x3f317217, v102
	v_mul_f32_e32 v111, 0x3f317217, v103
	v_fma_f32 v104, v96, s75, -v104
	v_fma_f32 v105, v97, s75, -v105
	v_fma_f32 v106, v98, s75, -v106
	v_fma_f32 v107, v99, s75, -v107
	v_fma_f32 v108, v100, s75, -v108
	v_fma_f32 v109, v101, s75, -v109
	v_fma_f32 v110, v102, s75, -v110
	v_fma_f32 v111, v103, s75, -v111
	v_fmac_f32_e32 v104, 0x3377d1cf, v96
	v_fmac_f32_e32 v105, 0x3377d1cf, v97
	v_fmac_f32_e32 v106, 0x3377d1cf, v98
	v_fmac_f32_e32 v107, 0x3377d1cf, v99
	v_fmac_f32_e32 v108, 0x3377d1cf, v100
	v_fmac_f32_e32 v109, 0x3377d1cf, v101
	v_fmac_f32_e32 v110, 0x3377d1cf, v102
	v_fmac_f32_e32 v111, 0x3377d1cf, v103
	v_fmac_f32_e32 v104, 0x3f317217, v96
	v_fmac_f32_e32 v105, 0x3f317217, v97
	v_fmac_f32_e32 v106, 0x3f317217, v98
	v_fmac_f32_e32 v107, 0x3f317217, v99
	v_fmac_f32_e32 v108, 0x3f317217, v100
	v_fmac_f32_e32 v109, 0x3f317217, v101
	v_fmac_f32_e32 v110, 0x3f317217, v102
	v_fmac_f32_e32 v111, 0x3f317217, v103
	v_add_f32_e32 v60, v60, v104
	v_add_f32_e32 v62, v62, v105
	v_add_f32_e32 v64, v64, v106
	v_add_f32_e32 v66, v66, v107
	v_add_f32_e32 v68, v68, v108
	v_add_f32_e32 v70, v70, v109
	v_add_f32_e32 v72, v72, v110
	v_add_f32_e32 v74, v74, v111
	v_cndmask_b32_e32 v60, 0, v60, vcc
	v_cndmask_b32_e64 v62, 0, v62, s[14:15]
	v_cndmask_b32_e64 v64, 0, v64, s[16:17]
	v_cndmask_b32_e64 v66, 0, v66, s[18:19]
	v_cndmask_b32_e64 v68, 0, v68, s[20:21]
	v_cndmask_b32_e64 v70, 0, v70, s[22:23]
	v_cndmask_b32_e64 v72, 0, v72, s[24:25]
	v_cndmask_b32_e64 v74, 0, v74, s[26:27]
	v_add_f32_e32 v58, 0, v60
	v_add_f32_e32 v58, v58, v62
	v_add_f32_e32 v58, v58, v64
	v_add_f32_e32 v58, v58, v66
	v_add_f32_e32 v58, v58, v68
	v_add_f32_e32 v58, v58, v70
	v_add_f32_e32 v58, v58, v72
	v_add_f32_e32 v58, v58, v74
	ds_bpermute_b32 v61, v78, v58
	v_mov_b32_e32 v73, v74
	v_mov_b32_e32 v71, v72
	v_mov_b32_e32 v69, v70
	v_mov_b32_e32 v67, v68
	s_waitcnt lgkmcnt(0)
; __device__ __forceinline__ unsigned pack2(float a, float b) { const f32v2_ v = {a, b}; const bf16v2_ r = __builtin_convertvector(v, bf16v2_); return __builtin_bit_cast(unsigned, r); }
; __device__ __forceinline__ float shfl_idx(float v, int srclane) { return __int_as_float(__builtin_amdgcn_ds_bpermute(srclane << 2, __float_as_int(v))); }
; __device__ __forceinline__ void attn_phase(const Params& p, char* shmc, int tid, int wv) {
;     ...
;         float tot = ptot;
; #pragma unroll
;         for (int o = 1; o < 8; o <<= 1) { const float v = shfl_idx(tot, lane + o); if (part + o < 8) tot += v; }
;         float running = carry - (tot - ptot);
;         float a[8];
; #pragma unroll
;         for (int i = 7; i >= 0; --i) {
;           const bool valid = (kpos0 + i) < qpos;
;           a[i] = valid ? __expf(z[i] - sp[i] + running) : 0.f;
;           running -= sp[i];
;         }
;         const float all = shfl_idx(tot, lane & ~7);
;         carry -= all;
;         *(uint4*)&Ps[row * 72 + part * 8] = make_uint4(pack2(a[0], a[1]), pack2(a[2], a[3]), pack2(a[4], a[5]), pack2(a[6], a[7]));
;       }
;       __syncthreads();
;       {
;         const int ntb = (wv >> 2) * 4;
; #pragma unroll
;         for (int kk = 0; kk < 2; ++kk) {
;           const bf16x8 a = *(const bf16x8*)&Ps[(16 * mt + r) * 72 + kk * 32 + quad * 8];
; #pragma unroll
;           for (int i = 0; i < 4; ++i) {
;             const bf16x8 b = *(const bf16x8*)&Vt[(16 * (ntb + i) + r) * 72 + kk * 32 + quad * 8];
;             oacc[i] = __builtin_amdgcn_mfma_f32_16x16x32_bf16(a, b, oacc[i], 0, 0, 0);
;           }
;         }
;       }
;       const int more = __syncthreads_or(carry > -120.f);
;       if (!more) break;
	v_add_f32_e32 v61, v58, v61
	v_cndmask_b32_e64 v61, v61, v58, s[8:9]
	ds_bpermute_b32 v63, v79, v61
	v_mov_b32_e32 v65, v66
	s_bitcmp1_b32 exec_hi, 0
	s_waitcnt lgkmcnt(0)
	v_add_f32_e32 v63, v61, v63
	v_cndmask_b32_e64 v61, v61, v63, s[10:11]
	ds_bpermute_b32 v63, v80, v61
	s_waitcnt lgkmcnt(0)
	v_add_f32_e32 v63, v61, v63
	v_cndmask_b32_e64 v94, v61, v63, s[12:13]
	v_sub_f32_e32 v75, v94, v58
	v_mov_b32_e32 v58, v39
	v_pk_add_f32 v[92:93], v[58:59], v[74:75] neg_lo:[0,1] neg_hi:[0,1]
	v_mov_b32_e32 v63, v64
	v_add_f32_e32 v39, v92, v93
	v_mul_f32_e32 v39, 0x3fb8aa3b, v39
	v_exp_f32_e32 v39, v39
	v_mov_b32_e32 v61, v62
	v_cndmask_b32_e64 v58, 0, v39, s[26:27]
	v_mov_b32_e32 v39, v93
	v_pk_add_f32 v[38:39], v[38:39], v[72:73] neg_lo:[0,1] neg_hi:[0,1]
	s_nop 0
	v_add_f32_e32 v38, v38, v39
	v_mul_f32_e32 v38, 0x3fb8aa3b, v38
	v_exp_f32_e32 v38, v38
	s_nop 0
	v_cndmask_b32_e64 v73, 0, v38, s[24:25]
	v_mov_b32_e32 v38, v37
	v_pk_add_f32 v[38:39], v[38:39], v[70:71] neg_lo:[0,1] neg_hi:[0,1]
	s_nop 0
	v_add_f32_e32 v37, v38, v39
	v_mul_f32_e32 v37, 0x3fb8aa3b, v37
	v_exp_f32_e32 v37, v37
	s_nop 0
	v_cndmask_b32_e64 v38, 0, v37, s[22:23]
	v_mov_b32_e32 v37, v39
	v_pk_add_f32 v[36:37], v[36:37], v[68:69] neg_lo:[0,1] neg_hi:[0,1]
	s_nop 0
	v_add_f32_e32 v36, v36, v37
	v_mul_f32_e32 v36, 0x3fb8aa3b, v36
	v_exp_f32_e32 v36, v36
	s_nop 0
	v_cndmask_b32_e64 v39, 0, v36, s[20:21]
	v_mov_b32_e32 v36, v35
	v_pk_add_f32 v[36:37], v[36:37], v[66:67] neg_lo:[0,1] neg_hi:[0,1]
	s_nop 0
	v_add_f32_e32 v35, v36, v37
	v_mul_f32_e32 v35, 0x3fb8aa3b, v35
	v_exp_f32_e32 v35, v35
	s_nop 0
	v_cndmask_b32_e64 v36, 0, v35, s[18:19]
	v_mov_b32_e32 v35, v37
	v_pk_add_f32 v[34:35], v[34:35], v[64:65] neg_lo:[0,1] neg_hi:[0,1]
	s_nop 0
	v_add_f32_e32 v34, v34, v35
	v_mul_f32_e32 v34, 0x3fb8aa3b, v34
	v_exp_f32_e32 v34, v34
	s_nop 0
	v_cndmask_b32_e64 v37, 0, v34, s[16:17]
	v_mov_b32_e32 v34, v33
	v_pk_add_f32 v[34:35], v[34:35], v[62:63] neg_lo:[0,1] neg_hi:[0,1]
	s_nop 0
	v_add_f32_e32 v33, v34, v35
	v_mul_f32_e32 v33, 0x3fb8aa3b, v33
	v_exp_f32_e32 v33, v33
	s_nop 0
	v_cndmask_b32_e64 v34, 0, v33, s[14:15]
	v_mov_b32_e32 v33, v35
	v_pk_add_f32 v[32:33], v[32:33], v[60:61] neg_lo:[0,1] neg_hi:[0,1]
	v_cvt_pk_bf16_f32 v35, v73, v58
	v_add_f32_e32 v32, v32, v33
	v_mul_f32_e32 v32, 0x3fb8aa3b, v32
	v_exp_f32_e32 v32, v32
	v_cvt_pk_bf16_f32 v33, v37, v36
	ds_bpermute_b32 v60, v53, v94
	s_mov_b32 s14, 0xc2d00000
	v_cndmask_b32_e32 v32, 0, v32, vcc
	v_cvt_pk_bf16_f32 v32, v32, v34
	v_cvt_pk_bf16_f32 v34, v39, v38
	ds_write_b128 v55, v[32:35]
	s_waitcnt lgkmcnt(0)
	s_barrier
	ds_read_b128 v[96:99], v76
	ds_read_b64_tr_b16 v[104:105], v86 offset:34816
	ds_read_b64_tr_b16 v[106:107], v86 offset:35904
	ds_read_b64_tr_b16 v[108:109], v86 offset:34848
	ds_read_b64_tr_b16 v[110:111], v86 offset:35936
	ds_read_b64_tr_b16 v[112:113], v86 offset:34880
	ds_read_b64_tr_b16 v[114:115], v86 offset:35968
	ds_read_b64_tr_b16 v[116:117], v86 offset:34912
	ds_read_b64_tr_b16 v[118:119], v86 offset:36000
	ds_read_b128 v[100:103], v76 offset:64
	ds_read_b64_tr_b16 v[120:121], v86 offset:43520
	ds_read_b64_tr_b16 v[122:123], v86 offset:44608
	ds_read_b64_tr_b16 v[124:125], v86 offset:43552
	ds_read_b64_tr_b16 v[126:127], v86 offset:44640
	ds_read_b64_tr_b16 v[128:129], v86 offset:43584
	ds_read_b64_tr_b16 v[130:131], v86 offset:44672
	ds_read_b64_tr_b16 v[132:133], v86 offset:43616
	ds_read_b64_tr_b16 v[134:135], v86 offset:44704
	v_sub_f32_e32 v59, v59, v60
	v_cmp_lt_f32_e32 vcc, s14, v59
	s_waitcnt lgkmcnt(15)
	v_mfma_f32_16x16x32_bf16 v[16:19], v[96:99], v[104:107], v[16:19]
	s_waitcnt lgkmcnt(13)
	v_mfma_f32_16x16x32_bf16 v[20:23], v[96:99], v[108:111], v[20:23]
	s_waitcnt lgkmcnt(11)
	v_mfma_f32_16x16x32_bf16 v[24:27], v[96:99], v[112:115], v[24:27]
	s_waitcnt lgkmcnt(9)
	v_mfma_f32_16x16x32_bf16 v[28:31], v[96:99], v[116:119], v[28:31]
	s_waitcnt lgkmcnt(6)
	v_mfma_f32_16x16x32_bf16 v[16:19], v[100:103], v[120:123], v[16:19]
	s_waitcnt lgkmcnt(4)
	v_mfma_f32_16x16x32_bf16 v[20:23], v[100:103], v[124:127], v[20:23]
	s_waitcnt lgkmcnt(2)
	v_mfma_f32_16x16x32_bf16 v[24:27], v[100:103], v[128:131], v[24:27]
	s_waitcnt lgkmcnt(0)
	v_mfma_f32_16x16x32_bf16 v[28:31], v[100:103], v[132:135], v[28:31]
	s_cmp_lg_u64 vcc, 0
	s_cselect_b32 s16, 1, 0
	v_mov_b32_e32 v32, s16
	s_andn2_b64 vcc, exec, s[94:95]
	s_cbranch_vccnz .Lat_310B
	s_and_saveexec_b64 s[14:15], s[4:5]
	v_mov_b32_e32 v32, s16
	ds_write_b32 v213, v32
	s_or_b64 exec, exec, s[14:15]
	s_waitcnt lgkmcnt(0)
	s_barrier
	s_and_saveexec_b64 s[14:15], s[98:99]
	s_cbranch_execz .Lat_309B
	v_mbcnt_lo_u32_b32 v32, exec_lo, 0
	v_mbcnt_hi_u32_b32 v32, exec_hi, v32
	v_cmp_eq_u32_e32 vcc, 0, v32
	s_and_b64 exec, exec, vcc
	s_cbranch_execz .Lat_309B
	v_mov_b32_e32 v32, s16
	ds_or_b32 v213, v32
	s_branch .Lat_309B
